# GEMM unit start: 128 accumulator zeroing v_mov_b32 replaced by 64 v_mov_b64 per unit
# speedup vs baseline: 1.0086x; 1.0086x over previous
; template <class Epi, class Sched, bool ALIGN_EPI = false, bool SP2 = false>
; __device__ __forceinline__ void gemm_phase(PG8_LAS unsigned char* lds, const Gemm g, const Sched& S, const Epi& E) {
;     ...
;         const bool has_next = S.next(ui + 1, nxt);
;         const char* nA = has_next ? (const char*)g.A + (size_t)(nxt.pm & g.pm_mask) * tstep : cA; const char* nB = has_next ? (const char*)g.Bt + (size_t)nxt.pn * tstep : cB;
;     ...
; #pragma unroll
;         for (int a = 0; a < 2; ++a)
; #pragma unroll
;             for (int b = 0; b < 2; ++b)
; #pragma unroll
;                 for (int m = 0; m < 4; ++m)
; #pragma unroll
;                     for (int n = 0; n < 2; ++n) acc[a][b][m][n] = (f32x4){0.f, 0.f, 0.f, 0.f};
.LBB0_94:
	s_ashr_i32 s45, s44, 31
	s_lshl_b64 s[2:3], s[44:45], 20
	s_add_u32 s46, s70, s2
	s_addc_u32 s47, s71, s3
	s_and_b64 s[2:3], s[40:41], exec
	s_cselect_b32 s45, s47, s51
	s_cselect_b32 s61, s46, s50
	s_ashr_i32 s43, s42, 31
	s_lshl_b64 s[2:3], s[42:43], 20
	s_add_u32 s48, s4, s2
	s_addc_u32 s49, s5, s3
	s_and_b64 s[2:3], s[40:41], exec
	s_cselect_b32 s43, s49, s25
	s_cselect_b32 s64, s48, s24
	s_add_u32 s65, s24, 0x100
	s_addc_u32 s66, s25, 0
	s_add_u32 s50, s50, 0x80080
	v_mov_b32_e32 v2, 0
	s_addc_u32 s51, s51, 0
	s_mov_b32 s67, -2
	v_mov_b64_e32 v[2:3], 0
	v_mov_b64_e32 v[4:5], 0
	v_mov_b64_e32 v[6:7], 0
	v_mov_b64_e32 v[8:9], 0
	v_mov_b64_e32 v[10:11], 0
	v_mov_b64_e32 v[12:13], 0
	v_mov_b64_e32 v[14:15], 0
	v_mov_b64_e32 v[16:17], 0
	v_mov_b64_e32 v[18:19], 0
	v_mov_b64_e32 v[20:21], 0
	v_mov_b64_e32 v[22:23], 0
	v_mov_b64_e32 v[24:25], 0
	v_mov_b64_e32 v[26:27], 0
	v_mov_b64_e32 v[28:29], 0
	v_mov_b64_e32 v[30:31], 0
	v_mov_b64_e32 v[32:33], 0
	v_mov_b64_e32 v[34:35], 0
	v_mov_b64_e32 v[36:37], 0
	v_mov_b64_e32 v[38:39], 0
	v_mov_b64_e32 v[40:41], 0
	v_mov_b64_e32 v[42:43], 0
	v_mov_b64_e32 v[44:45], 0
	v_mov_b64_e32 v[46:47], 0
	v_mov_b64_e32 v[48:49], 0
	v_mov_b64_e32 v[50:51], 0
	v_mov_b64_e32 v[52:53], 0
	v_mov_b64_e32 v[54:55], 0
	v_mov_b64_e32 v[56:57], 0
	v_mov_b64_e32 v[58:59], 0
	v_mov_b64_e32 v[60:61], 0
	v_mov_b64_e32 v[62:63], 0
	v_mov_b64_e32 v[64:65], 0
	v_mov_b64_e32 v[66:67], 0
	v_mov_b64_e32 v[68:69], 0
	v_mov_b64_e32 v[70:71], 0
	v_mov_b64_e32 v[72:73], 0
	v_mov_b64_e32 v[74:75], 0
	v_mov_b64_e32 v[76:77], 0
	v_mov_b64_e32 v[78:79], 0
	v_mov_b64_e32 v[80:81], 0
	v_mov_b64_e32 v[82:83], 0
	v_mov_b64_e32 v[84:85], 0
	v_mov_b64_e32 v[86:87], 0
	v_mov_b64_e32 v[88:89], 0
	v_mov_b64_e32 v[90:91], 0
	v_mov_b64_e32 v[92:93], 0
	v_mov_b64_e32 v[94:95], 0
	v_mov_b64_e32 v[96:97], 0
	v_mov_b64_e32 v[98:99], 0
	v_mov_b64_e32 v[100:101], 0
	v_mov_b64_e32 v[102:103], 0
	v_mov_b64_e32 v[104:105], 0
	v_mov_b64_e32 v[106:107], 0
	v_mov_b64_e32 v[108:109], 0
	v_mov_b64_e32 v[110:111], 0
	v_mov_b64_e32 v[112:113], 0
	v_mov_b64_e32 v[130:131], 0
	v_mov_b64_e32 v[132:133], 0
	v_mov_b64_e32 v[134:135], 0
	v_mov_b64_e32 v[136:137], 0
	v_mov_b64_e32 v[138:139], 0
	v_mov_b64_e32 v[140:141], 0
	v_mov_b64_e32 v[142:143], 0
	v_mov_b64_e32 v[144:145], 0

; template <class Epi, class Sched, bool ALIGN_EPI = false, bool SP2 = false>
; __device__ __forceinline__ void gemm_phase(PG8_LAS unsigned char* lds, const Gemm g, const Sched& S, const Epi& E) {
;     ...
;         const bool has_next = S.next(ui + 1, nxt);
;         const char* nA = has_next ? (const char*)g.A + (size_t)(nxt.pm & g.pm_mask) * tstep : cA; const char* nB = has_next ? (const char*)g.Bt + (size_t)nxt.pn * tstep : cB;
;     ...
; #pragma unroll
;         for (int a = 0; a < 2; ++a)
; #pragma unroll
;             for (int b = 0; b < 2; ++b)
; #pragma unroll
;                 for (int m = 0; m < 4; ++m)
; #pragma unroll
;                     for (int n = 0; n < 2; ++n) acc[a][b][m][n] = (f32x4){0.f, 0.f, 0.f, 0.f};
.LBB0_308:
	s_ashr_i32 s55, s54, 31
	s_lshl_b64 s[2:3], s[54:55], 20
	s_add_u32 s56, s70, s2
	s_addc_u32 s57, s71, s3
	s_and_b64 s[2:3], s[42:43], exec
	s_cselect_b32 s5, s57, s25
	s_cselect_b32 s6, s56, s24
	s_ashr_i32 s53, s52, 31
	s_lshl_b64 s[2:3], s[52:53], 20
	s_add_u32 s60, s58, s2
	s_addc_u32 s61, s59, s3
	s_and_b64 s[2:3], s[42:43], exec
	s_cselect_b32 s7, s61, s13
	s_cselect_b32 s8, s60, s12
	s_add_u32 s9, s12, 0x100
	s_addc_u32 s30, s13, 0
	s_add_u32 s12, s24, 0x80080
	v_mov_b32_e32 v2, 0
	s_addc_u32 s13, s25, 0
	s_mov_b32 s53, -2
	v_mov_b64_e32 v[2:3], 0
	v_mov_b64_e32 v[4:5], 0
	v_mov_b64_e32 v[6:7], 0
	v_mov_b64_e32 v[8:9], 0
	v_mov_b64_e32 v[10:11], 0
	v_mov_b64_e32 v[12:13], 0
	v_mov_b64_e32 v[14:15], 0
	v_mov_b64_e32 v[16:17], 0
	v_mov_b64_e32 v[18:19], 0
	v_mov_b64_e32 v[20:21], 0
	v_mov_b64_e32 v[22:23], 0
	v_mov_b64_e32 v[24:25], 0
	v_mov_b64_e32 v[26:27], 0
	v_mov_b64_e32 v[28:29], 0
	v_mov_b64_e32 v[30:31], 0
	v_mov_b64_e32 v[32:33], 0
	v_mov_b64_e32 v[34:35], 0
	v_mov_b64_e32 v[36:37], 0
	v_mov_b64_e32 v[38:39], 0
	v_mov_b64_e32 v[40:41], 0
	v_mov_b64_e32 v[42:43], 0
	v_mov_b64_e32 v[44:45], 0
	v_mov_b64_e32 v[46:47], 0
	v_mov_b64_e32 v[48:49], 0
	v_mov_b64_e32 v[50:51], 0
	v_mov_b64_e32 v[52:53], 0
	v_mov_b64_e32 v[54:55], 0
	v_mov_b64_e32 v[56:57], 0
	v_mov_b64_e32 v[58:59], 0
	v_mov_b64_e32 v[60:61], 0
	v_mov_b64_e32 v[62:63], 0
	v_mov_b64_e32 v[64:65], 0
	v_mov_b64_e32 v[66:67], 0
	v_mov_b64_e32 v[68:69], 0
	v_mov_b64_e32 v[70:71], 0
	v_mov_b64_e32 v[72:73], 0
	v_mov_b64_e32 v[74:75], 0
	v_mov_b64_e32 v[76:77], 0
	v_mov_b64_e32 v[78:79], 0
	v_mov_b64_e32 v[80:81], 0
	v_mov_b64_e32 v[82:83], 0
	v_mov_b64_e32 v[84:85], 0
	v_mov_b64_e32 v[86:87], 0
	v_mov_b64_e32 v[88:89], 0
	v_mov_b64_e32 v[90:91], 0
	v_mov_b64_e32 v[92:93], 0
	v_mov_b64_e32 v[94:95], 0
	v_mov_b64_e32 v[96:97], 0
	v_mov_b64_e32 v[98:99], 0
	v_mov_b64_e32 v[100:101], 0
	v_mov_b64_e32 v[102:103], 0
	v_mov_b64_e32 v[104:105], 0
	v_mov_b64_e32 v[106:107], 0
	v_mov_b64_e32 v[108:109], 0
	v_mov_b64_e32 v[110:111], 0
	v_mov_b64_e32 v[112:113], 0
	v_mov_b64_e32 v[114:115], 0
	v_mov_b64_e32 v[116:117], 0
	v_mov_b64_e32 v[118:119], 0
	v_mov_b64_e32 v[120:121], 0
	v_mov_b64_e32 v[122:123], 0
	v_mov_b64_e32 v[124:125], 0
	v_mov_b64_e32 v[126:127], 0
	v_mov_b64_e32 v[128:129], 0

; template <class Epi, class Sched, bool ALIGN_EPI = false, bool SP2 = false>
; __device__ __forceinline__ void gemm_phase(PG8_LAS unsigned char* lds, const Gemm g, const Sched& S, const Epi& E) {
;     ...
;         const bool has_next = S.next(ui + 1, nxt);
;         const char* nA = has_next ? (const char*)g.A + (size_t)(nxt.pm & g.pm_mask) * tstep : cA; const char* nB = has_next ? (const char*)g.Bt + (size_t)nxt.pn * tstep : cB;
;     ...
; #pragma unroll
;         for (int a = 0; a < 2; ++a)
; #pragma unroll
;             for (int b = 0; b < 2; ++b)
; #pragma unroll
;                 for (int m = 0; m < 4; ++m)
; #pragma unroll
;                     for (int n = 0; n < 2; ++n) acc[a][b][m][n] = (f32x4){0.f, 0.f, 0.f, 0.f};
.LBB0_350:
	s_ashr_i32 s51, s50, 31
	s_lshl_b64 s[2:3], s[50:51], 20
	s_add_u32 s52, s70, s2
	s_addc_u32 s53, s71, s3
	s_and_b64 s[2:3], s[40:41], exec
	s_cselect_b32 s5, s53, s25
	s_cselect_b32 s6, s52, s24
	s_ashr_i32 s49, s48, 31
	s_lshl_b64 s[2:3], s[48:49], 20
	s_add_u32 s54, s30, s2
	s_addc_u32 s55, s56, s3
	s_and_b64 s[2:3], s[40:41], exec
	s_cselect_b32 s7, s55, s13
	s_cselect_b32 s8, s54, s12
	s_add_u32 s9, s12, 0x100
	s_addc_u32 s49, s13, 0
	s_add_u32 s12, s24, 0x80080
	v_mov_b32_e32 v10, 0
	s_addc_u32 s13, s25, 0
	s_mov_b32 s51, -2
	v_mov_b64_e32 v[10:11], 0
	v_mov_b64_e32 v[12:13], 0
	v_mov_b64_e32 v[14:15], 0
	v_mov_b64_e32 v[16:17], 0
	v_mov_b64_e32 v[18:19], 0
	v_mov_b64_e32 v[20:21], 0
	v_mov_b64_e32 v[22:23], 0
	v_mov_b64_e32 v[24:25], 0
	v_mov_b64_e32 v[26:27], 0
	v_mov_b64_e32 v[28:29], 0
	v_mov_b64_e32 v[30:31], 0
	v_mov_b64_e32 v[32:33], 0
	v_mov_b64_e32 v[34:35], 0
	v_mov_b64_e32 v[36:37], 0
	v_mov_b64_e32 v[38:39], 0
	v_mov_b64_e32 v[40:41], 0
	v_mov_b64_e32 v[42:43], 0
	v_mov_b64_e32 v[44:45], 0
	v_mov_b64_e32 v[46:47], 0
	v_mov_b64_e32 v[48:49], 0
	v_mov_b64_e32 v[50:51], 0
	v_mov_b64_e32 v[52:53], 0
	v_mov_b64_e32 v[54:55], 0
	v_mov_b64_e32 v[56:57], 0
	v_mov_b64_e32 v[58:59], 0
	v_mov_b64_e32 v[60:61], 0
	v_mov_b64_e32 v[62:63], 0
	v_mov_b64_e32 v[64:65], 0
	v_mov_b64_e32 v[66:67], 0
	v_mov_b64_e32 v[68:69], 0
	v_mov_b64_e32 v[70:71], 0
	v_mov_b64_e32 v[72:73], 0
	v_mov_b64_e32 v[74:75], 0
	v_mov_b64_e32 v[76:77], 0
	v_mov_b64_e32 v[78:79], 0
	v_mov_b64_e32 v[80:81], 0
	v_mov_b64_e32 v[82:83], 0
	v_mov_b64_e32 v[84:85], 0
	v_mov_b64_e32 v[86:87], 0
	v_mov_b64_e32 v[88:89], 0
	v_mov_b64_e32 v[90:91], 0
	v_mov_b64_e32 v[92:93], 0
	v_mov_b64_e32 v[94:95], 0
	v_mov_b64_e32 v[96:97], 0
	v_mov_b64_e32 v[98:99], 0
	v_mov_b64_e32 v[100:101], 0
	v_mov_b64_e32 v[102:103], 0
	v_mov_b64_e32 v[104:105], 0
	v_mov_b64_e32 v[106:107], 0
	v_mov_b64_e32 v[108:109], 0
	v_mov_b64_e32 v[110:111], 0
	v_mov_b64_e32 v[112:113], 0
	v_mov_b64_e32 v[114:115], 0
	v_mov_b64_e32 v[116:117], 0
	v_mov_b64_e32 v[118:119], 0
	v_mov_b64_e32 v[120:121], 0
	v_mov_b64_e32 v[122:123], 0
	v_mov_b64_e32 v[124:125], 0
	v_mov_b64_e32 v[126:127], 0
	v_mov_b64_e32 v[128:129], 0
	v_mov_b64_e32 v[130:131], 0
	v_mov_b64_e32 v[132:133], 0
	v_mov_b64_e32 v[134:135], 0
	v_mov_b64_e32 v[136:137], 0
